# G2 gather loop as one 64-row stream per token half-list with a rolling window: next batch's row fetched into the registers just freed (32 loads always in flight)
# speedup vs baseline: 1.0130x; 1.0079x over previous
.LBB0_1093:
	ds_read_b128 v[88:91], v101
	ds_read_b128 v[84:87], v101 offset:16
	ds_read_b128 v[80:83], v101 offset:32
	ds_read_b128 v[76:79], v101 offset:48
	ds_read_b128 v[242:245], v101 offset:128
	ds_read_b128 v[246:249], v101 offset:144
	ds_read_b128 v[238:241], v101 offset:160
	ds_read_b64 v[224:225], v101 offset:176
	ds_read_b64 v[104:105], v101 offset:184
	s_setprio 1
	s_waitcnt lgkmcnt(8)
	v_and_b32_e32 v138, 0xffff, v88
	v_mad_u32_u24 v142, v138, s22, v117
	v_mad_u32_u24 v138, v138, s22, v116
	global_load_dwordx4 v[138:141], v138, s[2:3]
	global_load_dwordx2 v[142:143], v142, s[2:3]
	v_and_b32_e32 v144, 0xffff, v89
	v_mad_u32_u24 v148, v144, s22, v117
	v_mad_u32_u24 v144, v144, s22, v116
	global_load_dwordx4 v[144:147], v144, s[2:3]
	global_load_dwordx2 v[148:149], v148, s[2:3]
	v_and_b32_e32 v150, 0xffff, v90
	v_mad_u32_u24 v154, v150, s22, v117
	v_mad_u32_u24 v150, v150, s22, v116
	global_load_dwordx4 v[150:153], v150, s[2:3]
	global_load_dwordx2 v[154:155], v154, s[2:3]
	v_and_b32_e32 v156, 0xffff, v91
	v_mad_u32_u24 v160, v156, s22, v117
	v_mad_u32_u24 v156, v156, s22, v116
	global_load_dwordx4 v[156:159], v156, s[2:3]
	global_load_dwordx2 v[160:161], v160, s[2:3]
	s_waitcnt lgkmcnt(7)
	v_and_b32_e32 v162, 0xffff, v84
	v_mad_u32_u24 v166, v162, s22, v117
	v_mad_u32_u24 v162, v162, s22, v116
	global_load_dwordx4 v[162:165], v162, s[2:3]
	global_load_dwordx2 v[166:167], v166, s[2:3]
	v_and_b32_e32 v168, 0xffff, v85
	v_mad_u32_u24 v172, v168, s22, v117
	v_mad_u32_u24 v168, v168, s22, v116
	global_load_dwordx4 v[168:171], v168, s[2:3]
	global_load_dwordx2 v[172:173], v172, s[2:3]
	v_and_b32_e32 v174, 0xffff, v86
	v_mad_u32_u24 v178, v174, s22, v117
	v_mad_u32_u24 v174, v174, s22, v116
	global_load_dwordx4 v[174:177], v174, s[2:3]
	global_load_dwordx2 v[178:179], v178, s[2:3]
	v_and_b32_e32 v180, 0xffff, v87
	v_mad_u32_u24 v184, v180, s22, v117
	v_mad_u32_u24 v180, v180, s22, v116
	global_load_dwordx4 v[180:183], v180, s[2:3]
	global_load_dwordx2 v[184:185], v184, s[2:3]
	s_waitcnt lgkmcnt(6)
	v_and_b32_e32 v186, 0xffff, v80
	v_mad_u32_u24 v190, v186, s22, v117
	v_mad_u32_u24 v186, v186, s22, v116
	global_load_dwordx4 v[186:189], v186, s[2:3]
	global_load_dwordx2 v[190:191], v190, s[2:3]
	v_and_b32_e32 v192, 0xffff, v81
	v_mad_u32_u24 v196, v192, s22, v117
	v_mad_u32_u24 v192, v192, s22, v116
	global_load_dwordx4 v[192:195], v192, s[2:3]
	global_load_dwordx2 v[196:197], v196, s[2:3]
	v_and_b32_e32 v198, 0xffff, v82
	v_mad_u32_u24 v202, v198, s22, v117
	v_mad_u32_u24 v198, v198, s22, v116
	global_load_dwordx4 v[198:201], v198, s[2:3]
	global_load_dwordx2 v[202:203], v202, s[2:3]
	v_and_b32_e32 v204, 0xffff, v83
	v_mad_u32_u24 v208, v204, s22, v117
	v_mad_u32_u24 v204, v204, s22, v116
	global_load_dwordx4 v[204:207], v204, s[2:3]
	global_load_dwordx2 v[208:209], v208, s[2:3]
	s_waitcnt lgkmcnt(5)
	v_and_b32_e32 v210, 0xffff, v76
	v_mad_u32_u24 v214, v210, s22, v117
	v_mad_u32_u24 v210, v210, s22, v116
	global_load_dwordx4 v[210:213], v210, s[2:3]
	global_load_dwordx2 v[214:215], v214, s[2:3]
	v_and_b32_e32 v216, 0xffff, v77
	v_mad_u32_u24 v220, v216, s22, v117
	v_mad_u32_u24 v216, v216, s22, v116
	global_load_dwordx4 v[216:219], v216, s[2:3]
	global_load_dwordx2 v[220:221], v220, s[2:3]
	v_and_b32_e32 v22, 0xffff, v78
	v_mad_u32_u24 v26, v22, s22, v117
	v_mad_u32_u24 v22, v22, s22, v116
	global_load_dwordx4 v[22:25], v22, s[2:3]
	global_load_dwordx2 v[26:27], v26, s[2:3]
	v_and_b32_e32 v16, 0xffff, v79
	v_mad_u32_u24 v20, v16, s22, v117
	v_mad_u32_u24 v16, v16, s22, v116
	global_load_dwordx4 v[16:19], v16, s[2:3]
	global_load_dwordx2 v[20:21], v20, s[2:3]
	s_waitcnt vmcnt(30)
	s_waitcnt lgkmcnt(0)
	v_cvt_scalef32_pk32_f16_fp6 v[0:15], v[138:143], 1.0
	v_and_b32_e32 v138, 0xffff, v242
	v_mad_u32_u24 v142, v138, s22, v117
	v_mad_u32_u24 v138, v138, s22, v116
	global_load_dwordx4 v[138:141], v138, s[2:3]
	global_load_dwordx2 v[142:143], v142, s[2:3]
	v_pk_fma_f16 v133, v88, v0, v133 op_sel:[1,0,0]
	v_pk_fma_f16 v131, v88, v1, v131 op_sel:[1,0,0]
	v_pk_fma_f16 v129, v88, v2, v129 op_sel:[1,0,0]
	v_pk_fma_f16 v128, v88, v3, v128 op_sel:[1,0,0]
	v_pk_fma_f16 v127, v88, v4, v127 op_sel:[1,0,0]
	v_pk_fma_f16 v125, v88, v5, v125 op_sel:[1,0,0]
	v_pk_fma_f16 v123, v88, v6, v123 op_sel:[1,0,0]
	v_pk_fma_f16 v121, v88, v7, v121 op_sel:[1,0,0]
	v_pk_fma_f16 v136, v88, v8, v136 op_sel:[1,0,0]
	v_pk_fma_f16 v135, v88, v9, v135 op_sel:[1,0,0]
	v_pk_fma_f16 v134, v88, v10, v134 op_sel:[1,0,0]
	v_pk_fma_f16 v132, v88, v11, v132 op_sel:[1,0,0]
	v_pk_fma_f16 v130, v88, v12, v130 op_sel:[1,0,0]
	v_pk_fma_f16 v126, v88, v13, v126 op_sel:[1,0,0]
	v_pk_fma_f16 v124, v88, v14, v124 op_sel:[1,0,0]
	v_pk_fma_f16 v122, v88, v15, v122 op_sel:[1,0,0]
	s_waitcnt vmcnt(30)
	v_cvt_scalef32_pk32_f16_fp6 v[0:15], v[144:149], 1.0
	v_and_b32_e32 v144, 0xffff, v243
	v_mad_u32_u24 v148, v144, s22, v117
	v_mad_u32_u24 v144, v144, s22, v116
	global_load_dwordx4 v[144:147], v144, s[2:3]
	global_load_dwordx2 v[148:149], v148, s[2:3]
	v_pk_fma_f16 v133, v89, v0, v133 op_sel:[1,0,0]
	v_pk_fma_f16 v131, v89, v1, v131 op_sel:[1,0,0]
	v_pk_fma_f16 v129, v89, v2, v129 op_sel:[1,0,0]
	v_pk_fma_f16 v128, v89, v3, v128 op_sel:[1,0,0]
	v_pk_fma_f16 v127, v89, v4, v127 op_sel:[1,0,0]
	v_pk_fma_f16 v125, v89, v5, v125 op_sel:[1,0,0]
	v_pk_fma_f16 v123, v89, v6, v123 op_sel:[1,0,0]
	v_pk_fma_f16 v121, v89, v7, v121 op_sel:[1,0,0]
	v_pk_fma_f16 v136, v89, v8, v136 op_sel:[1,0,0]
	v_pk_fma_f16 v135, v89, v9, v135 op_sel:[1,0,0]
	v_pk_fma_f16 v134, v89, v10, v134 op_sel:[1,0,0]
	v_pk_fma_f16 v132, v89, v11, v132 op_sel:[1,0,0]
	v_pk_fma_f16 v130, v89, v12, v130 op_sel:[1,0,0]
	v_pk_fma_f16 v126, v89, v13, v126 op_sel:[1,0,0]
	v_pk_fma_f16 v124, v89, v14, v124 op_sel:[1,0,0]
	v_pk_fma_f16 v122, v89, v15, v122 op_sel:[1,0,0]
	s_waitcnt vmcnt(30)
	v_cvt_scalef32_pk32_f16_fp6 v[0:15], v[150:155], 1.0
	v_and_b32_e32 v150, 0xffff, v244
	v_mad_u32_u24 v154, v150, s22, v117
	v_mad_u32_u24 v150, v150, s22, v116
	global_load_dwordx4 v[150:153], v150, s[2:3]
	global_load_dwordx2 v[154:155], v154, s[2:3]
	v_pk_fma_f16 v133, v90, v0, v133 op_sel:[1,0,0]
	v_pk_fma_f16 v131, v90, v1, v131 op_sel:[1,0,0]
	v_pk_fma_f16 v129, v90, v2, v129 op_sel:[1,0,0]
	v_pk_fma_f16 v128, v90, v3, v128 op_sel:[1,0,0]
	v_pk_fma_f16 v127, v90, v4, v127 op_sel:[1,0,0]
	v_pk_fma_f16 v125, v90, v5, v125 op_sel:[1,0,0]
	v_pk_fma_f16 v123, v90, v6, v123 op_sel:[1,0,0]
	v_pk_fma_f16 v121, v90, v7, v121 op_sel:[1,0,0]
	v_pk_fma_f16 v136, v90, v8, v136 op_sel:[1,0,0]
	v_pk_fma_f16 v135, v90, v9, v135 op_sel:[1,0,0]
	v_pk_fma_f16 v134, v90, v10, v134 op_sel:[1,0,0]
	v_pk_fma_f16 v132, v90, v11, v132 op_sel:[1,0,0]
	v_pk_fma_f16 v130, v90, v12, v130 op_sel:[1,0,0]
	v_pk_fma_f16 v126, v90, v13, v126 op_sel:[1,0,0]
	v_pk_fma_f16 v124, v90, v14, v124 op_sel:[1,0,0]
	v_pk_fma_f16 v122, v90, v15, v122 op_sel:[1,0,0]
	s_waitcnt vmcnt(30)
	v_cvt_scalef32_pk32_f16_fp6 v[0:15], v[156:161], 1.0
	v_and_b32_e32 v156, 0xffff, v245
	v_mad_u32_u24 v160, v156, s22, v117
	v_mad_u32_u24 v156, v156, s22, v116
	global_load_dwordx4 v[156:159], v156, s[2:3]
	global_load_dwordx2 v[160:161], v160, s[2:3]
	v_pk_fma_f16 v133, v91, v0, v133 op_sel:[1,0,0]
	v_pk_fma_f16 v131, v91, v1, v131 op_sel:[1,0,0]
	v_pk_fma_f16 v129, v91, v2, v129 op_sel:[1,0,0]
	v_pk_fma_f16 v128, v91, v3, v128 op_sel:[1,0,0]
	v_pk_fma_f16 v127, v91, v4, v127 op_sel:[1,0,0]
	v_pk_fma_f16 v125, v91, v5, v125 op_sel:[1,0,0]
	v_pk_fma_f16 v123, v91, v6, v123 op_sel:[1,0,0]
	v_pk_fma_f16 v121, v91, v7, v121 op_sel:[1,0,0]
	v_pk_fma_f16 v136, v91, v8, v136 op_sel:[1,0,0]
	v_pk_fma_f16 v135, v91, v9, v135 op_sel:[1,0,0]
	v_pk_fma_f16 v134, v91, v10, v134 op_sel:[1,0,0]
	v_pk_fma_f16 v132, v91, v11, v132 op_sel:[1,0,0]
	v_pk_fma_f16 v130, v91, v12, v130 op_sel:[1,0,0]
	v_pk_fma_f16 v126, v91, v13, v126 op_sel:[1,0,0]
	v_pk_fma_f16 v124, v91, v14, v124 op_sel:[1,0,0]
	v_pk_fma_f16 v122, v91, v15, v122 op_sel:[1,0,0]
	s_waitcnt vmcnt(30)
	v_cvt_scalef32_pk32_f16_fp6 v[0:15], v[162:167], 1.0
	v_and_b32_e32 v162, 0xffff, v246
	v_mad_u32_u24 v166, v162, s22, v117
	v_mad_u32_u24 v162, v162, s22, v116
	global_load_dwordx4 v[162:165], v162, s[2:3]
	global_load_dwordx2 v[166:167], v166, s[2:3]
	v_pk_fma_f16 v133, v84, v0, v133 op_sel:[1,0,0]
	v_pk_fma_f16 v131, v84, v1, v131 op_sel:[1,0,0]
	v_pk_fma_f16 v129, v84, v2, v129 op_sel:[1,0,0]
	v_pk_fma_f16 v128, v84, v3, v128 op_sel:[1,0,0]
	v_pk_fma_f16 v127, v84, v4, v127 op_sel:[1,0,0]
	v_pk_fma_f16 v125, v84, v5, v125 op_sel:[1,0,0]
	v_pk_fma_f16 v123, v84, v6, v123 op_sel:[1,0,0]
	v_pk_fma_f16 v121, v84, v7, v121 op_sel:[1,0,0]
	v_pk_fma_f16 v136, v84, v8, v136 op_sel:[1,0,0]
	v_pk_fma_f16 v135, v84, v9, v135 op_sel:[1,0,0]
	v_pk_fma_f16 v134, v84, v10, v134 op_sel:[1,0,0]
	v_pk_fma_f16 v132, v84, v11, v132 op_sel:[1,0,0]
	v_pk_fma_f16 v130, v84, v12, v130 op_sel:[1,0,0]
	v_pk_fma_f16 v126, v84, v13, v126 op_sel:[1,0,0]
	v_pk_fma_f16 v124, v84, v14, v124 op_sel:[1,0,0]
	v_pk_fma_f16 v122, v84, v15, v122 op_sel:[1,0,0]
	s_waitcnt vmcnt(30)
	v_cvt_scalef32_pk32_f16_fp6 v[0:15], v[168:173], 1.0
	v_and_b32_e32 v168, 0xffff, v247
	v_mad_u32_u24 v172, v168, s22, v117
	v_mad_u32_u24 v168, v168, s22, v116
	global_load_dwordx4 v[168:171], v168, s[2:3]
	global_load_dwordx2 v[172:173], v172, s[2:3]
	v_pk_fma_f16 v133, v85, v0, v133 op_sel:[1,0,0]
	v_pk_fma_f16 v131, v85, v1, v131 op_sel:[1,0,0]
	v_pk_fma_f16 v129, v85, v2, v129 op_sel:[1,0,0]
	v_pk_fma_f16 v128, v85, v3, v128 op_sel:[1,0,0]
	v_pk_fma_f16 v127, v85, v4, v127 op_sel:[1,0,0]
	v_pk_fma_f16 v125, v85, v5, v125 op_sel:[1,0,0]
	v_pk_fma_f16 v123, v85, v6, v123 op_sel:[1,0,0]
	v_pk_fma_f16 v121, v85, v7, v121 op_sel:[1,0,0]
	v_pk_fma_f16 v136, v85, v8, v136 op_sel:[1,0,0]
	v_pk_fma_f16 v135, v85, v9, v135 op_sel:[1,0,0]
	v_pk_fma_f16 v134, v85, v10, v134 op_sel:[1,0,0]
	v_pk_fma_f16 v132, v85, v11, v132 op_sel:[1,0,0]
	v_pk_fma_f16 v130, v85, v12, v130 op_sel:[1,0,0]
	v_pk_fma_f16 v126, v85, v13, v126 op_sel:[1,0,0]
	v_pk_fma_f16 v124, v85, v14, v124 op_sel:[1,0,0]
	v_pk_fma_f16 v122, v85, v15, v122 op_sel:[1,0,0]
	s_waitcnt vmcnt(30)
	v_cvt_scalef32_pk32_f16_fp6 v[0:15], v[174:179], 1.0
	v_and_b32_e32 v174, 0xffff, v248
	v_mad_u32_u24 v178, v174, s22, v117
	v_mad_u32_u24 v174, v174, s22, v116
	global_load_dwordx4 v[174:177], v174, s[2:3]
	global_load_dwordx2 v[178:179], v178, s[2:3]
	v_pk_fma_f16 v133, v86, v0, v133 op_sel:[1,0,0]
	v_pk_fma_f16 v131, v86, v1, v131 op_sel:[1,0,0]
	v_pk_fma_f16 v129, v86, v2, v129 op_sel:[1,0,0]
	v_pk_fma_f16 v128, v86, v3, v128 op_sel:[1,0,0]
	v_pk_fma_f16 v127, v86, v4, v127 op_sel:[1,0,0]
	v_pk_fma_f16 v125, v86, v5, v125 op_sel:[1,0,0]
	v_pk_fma_f16 v123, v86, v6, v123 op_sel:[1,0,0]
	v_pk_fma_f16 v121, v86, v7, v121 op_sel:[1,0,0]
	v_pk_fma_f16 v136, v86, v8, v136 op_sel:[1,0,0]
	v_pk_fma_f16 v135, v86, v9, v135 op_sel:[1,0,0]
	v_pk_fma_f16 v134, v86, v10, v134 op_sel:[1,0,0]
	v_pk_fma_f16 v132, v86, v11, v132 op_sel:[1,0,0]
	v_pk_fma_f16 v130, v86, v12, v130 op_sel:[1,0,0]
	v_pk_fma_f16 v126, v86, v13, v126 op_sel:[1,0,0]
	v_pk_fma_f16 v124, v86, v14, v124 op_sel:[1,0,0]
	v_pk_fma_f16 v122, v86, v15, v122 op_sel:[1,0,0]
	s_waitcnt vmcnt(30)
	v_cvt_scalef32_pk32_f16_fp6 v[0:15], v[180:185], 1.0
	v_and_b32_e32 v180, 0xffff, v249
	v_mad_u32_u24 v184, v180, s22, v117
	v_mad_u32_u24 v180, v180, s22, v116
	global_load_dwordx4 v[180:183], v180, s[2:3]
	global_load_dwordx2 v[184:185], v184, s[2:3]
	v_pk_fma_f16 v133, v87, v0, v133 op_sel:[1,0,0]
	v_pk_fma_f16 v131, v87, v1, v131 op_sel:[1,0,0]
	v_pk_fma_f16 v129, v87, v2, v129 op_sel:[1,0,0]
	v_pk_fma_f16 v128, v87, v3, v128 op_sel:[1,0,0]
	v_pk_fma_f16 v127, v87, v4, v127 op_sel:[1,0,0]
	v_pk_fma_f16 v125, v87, v5, v125 op_sel:[1,0,0]
	v_pk_fma_f16 v123, v87, v6, v123 op_sel:[1,0,0]
	v_pk_fma_f16 v121, v87, v7, v121 op_sel:[1,0,0]
	v_pk_fma_f16 v136, v87, v8, v136 op_sel:[1,0,0]
	v_pk_fma_f16 v135, v87, v9, v135 op_sel:[1,0,0]
	v_pk_fma_f16 v134, v87, v10, v134 op_sel:[1,0,0]
	v_pk_fma_f16 v132, v87, v11, v132 op_sel:[1,0,0]
	v_pk_fma_f16 v130, v87, v12, v130 op_sel:[1,0,0]
	v_pk_fma_f16 v126, v87, v13, v126 op_sel:[1,0,0]
	v_pk_fma_f16 v124, v87, v14, v124 op_sel:[1,0,0]
	v_pk_fma_f16 v122, v87, v15, v122 op_sel:[1,0,0]
	s_waitcnt vmcnt(30)
	v_cvt_scalef32_pk32_f16_fp6 v[0:15], v[186:191], 1.0
	v_and_b32_e32 v186, 0xffff, v238
	v_mad_u32_u24 v190, v186, s22, v117
	v_mad_u32_u24 v186, v186, s22, v116
	global_load_dwordx4 v[186:189], v186, s[2:3]
	global_load_dwordx2 v[190:191], v190, s[2:3]
	v_pk_fma_f16 v133, v80, v0, v133 op_sel:[1,0,0]
	v_pk_fma_f16 v131, v80, v1, v131 op_sel:[1,0,0]
	v_pk_fma_f16 v129, v80, v2, v129 op_sel:[1,0,0]
	v_pk_fma_f16 v128, v80, v3, v128 op_sel:[1,0,0]
	v_pk_fma_f16 v127, v80, v4, v127 op_sel:[1,0,0]
	v_pk_fma_f16 v125, v80, v5, v125 op_sel:[1,0,0]
	v_pk_fma_f16 v123, v80, v6, v123 op_sel:[1,0,0]
	v_pk_fma_f16 v121, v80, v7, v121 op_sel:[1,0,0]
	v_pk_fma_f16 v136, v80, v8, v136 op_sel:[1,0,0]
	v_pk_fma_f16 v135, v80, v9, v135 op_sel:[1,0,0]
	v_pk_fma_f16 v134, v80, v10, v134 op_sel:[1,0,0]
	v_pk_fma_f16 v132, v80, v11, v132 op_sel:[1,0,0]
	v_pk_fma_f16 v130, v80, v12, v130 op_sel:[1,0,0]
	v_pk_fma_f16 v126, v80, v13, v126 op_sel:[1,0,0]
	v_pk_fma_f16 v124, v80, v14, v124 op_sel:[1,0,0]
	v_pk_fma_f16 v122, v80, v15, v122 op_sel:[1,0,0]
	s_waitcnt vmcnt(30)
	v_cvt_scalef32_pk32_f16_fp6 v[0:15], v[192:197], 1.0
	v_and_b32_e32 v192, 0xffff, v239
	v_mad_u32_u24 v196, v192, s22, v117
	v_mad_u32_u24 v192, v192, s22, v116
	global_load_dwordx4 v[192:195], v192, s[2:3]
	global_load_dwordx2 v[196:197], v196, s[2:3]
	v_pk_fma_f16 v133, v81, v0, v133 op_sel:[1,0,0]
	v_pk_fma_f16 v131, v81, v1, v131 op_sel:[1,0,0]
	v_pk_fma_f16 v129, v81, v2, v129 op_sel:[1,0,0]
	v_pk_fma_f16 v128, v81, v3, v128 op_sel:[1,0,0]
	v_pk_fma_f16 v127, v81, v4, v127 op_sel:[1,0,0]
	v_pk_fma_f16 v125, v81, v5, v125 op_sel:[1,0,0]
	v_pk_fma_f16 v123, v81, v6, v123 op_sel:[1,0,0]
	v_pk_fma_f16 v121, v81, v7, v121 op_sel:[1,0,0]
	v_pk_fma_f16 v136, v81, v8, v136 op_sel:[1,0,0]
	v_pk_fma_f16 v135, v81, v9, v135 op_sel:[1,0,0]
	v_pk_fma_f16 v134, v81, v10, v134 op_sel:[1,0,0]
	v_pk_fma_f16 v132, v81, v11, v132 op_sel:[1,0,0]
	v_pk_fma_f16 v130, v81, v12, v130 op_sel:[1,0,0]
	v_pk_fma_f16 v126, v81, v13, v126 op_sel:[1,0,0]
	v_pk_fma_f16 v124, v81, v14, v124 op_sel:[1,0,0]
	v_pk_fma_f16 v122, v81, v15, v122 op_sel:[1,0,0]
	s_waitcnt vmcnt(30)
	v_cvt_scalef32_pk32_f16_fp6 v[0:15], v[198:203], 1.0
	v_and_b32_e32 v198, 0xffff, v240
	v_mad_u32_u24 v202, v198, s22, v117
	v_mad_u32_u24 v198, v198, s22, v116
	global_load_dwordx4 v[198:201], v198, s[2:3]
	global_load_dwordx2 v[202:203], v202, s[2:3]
	v_pk_fma_f16 v133, v82, v0, v133 op_sel:[1,0,0]
	v_pk_fma_f16 v131, v82, v1, v131 op_sel:[1,0,0]
	v_pk_fma_f16 v129, v82, v2, v129 op_sel:[1,0,0]
	v_pk_fma_f16 v128, v82, v3, v128 op_sel:[1,0,0]
	v_pk_fma_f16 v127, v82, v4, v127 op_sel:[1,0,0]
	v_pk_fma_f16 v125, v82, v5, v125 op_sel:[1,0,0]
	v_pk_fma_f16 v123, v82, v6, v123 op_sel:[1,0,0]
	v_pk_fma_f16 v121, v82, v7, v121 op_sel:[1,0,0]
	v_pk_fma_f16 v136, v82, v8, v136 op_sel:[1,0,0]
	v_pk_fma_f16 v135, v82, v9, v135 op_sel:[1,0,0]
	v_pk_fma_f16 v134, v82, v10, v134 op_sel:[1,0,0]
	v_pk_fma_f16 v132, v82, v11, v132 op_sel:[1,0,0]
	v_pk_fma_f16 v130, v82, v12, v130 op_sel:[1,0,0]
	v_pk_fma_f16 v126, v82, v13, v126 op_sel:[1,0,0]
	v_pk_fma_f16 v124, v82, v14, v124 op_sel:[1,0,0]
	v_pk_fma_f16 v122, v82, v15, v122 op_sel:[1,0,0]
	s_waitcnt vmcnt(30)
	v_cvt_scalef32_pk32_f16_fp6 v[0:15], v[204:209], 1.0
	v_and_b32_e32 v204, 0xffff, v241
	v_mad_u32_u24 v208, v204, s22, v117
	v_mad_u32_u24 v204, v204, s22, v116
	global_load_dwordx4 v[204:207], v204, s[2:3]
	global_load_dwordx2 v[208:209], v208, s[2:3]
	v_pk_fma_f16 v133, v83, v0, v133 op_sel:[1,0,0]
	v_pk_fma_f16 v131, v83, v1, v131 op_sel:[1,0,0]
	v_pk_fma_f16 v129, v83, v2, v129 op_sel:[1,0,0]
	v_pk_fma_f16 v128, v83, v3, v128 op_sel:[1,0,0]
	v_pk_fma_f16 v127, v83, v4, v127 op_sel:[1,0,0]
	v_pk_fma_f16 v125, v83, v5, v125 op_sel:[1,0,0]
	v_pk_fma_f16 v123, v83, v6, v123 op_sel:[1,0,0]
	v_pk_fma_f16 v121, v83, v7, v121 op_sel:[1,0,0]
	v_pk_fma_f16 v136, v83, v8, v136 op_sel:[1,0,0]
	v_pk_fma_f16 v135, v83, v9, v135 op_sel:[1,0,0]
	v_pk_fma_f16 v134, v83, v10, v134 op_sel:[1,0,0]
	v_pk_fma_f16 v132, v83, v11, v132 op_sel:[1,0,0]
	v_pk_fma_f16 v130, v83, v12, v130 op_sel:[1,0,0]
	v_pk_fma_f16 v126, v83, v13, v126 op_sel:[1,0,0]
	v_pk_fma_f16 v124, v83, v14, v124 op_sel:[1,0,0]
	v_pk_fma_f16 v122, v83, v15, v122 op_sel:[1,0,0]
	s_waitcnt vmcnt(30)
	v_cvt_scalef32_pk32_f16_fp6 v[0:15], v[210:215], 1.0
	v_and_b32_e32 v210, 0xffff, v224
	v_mad_u32_u24 v214, v210, s22, v117
	v_mad_u32_u24 v210, v210, s22, v116
	global_load_dwordx4 v[210:213], v210, s[2:3]
	global_load_dwordx2 v[214:215], v214, s[2:3]
	v_pk_fma_f16 v133, v76, v0, v133 op_sel:[1,0,0]
	v_pk_fma_f16 v131, v76, v1, v131 op_sel:[1,0,0]
	v_pk_fma_f16 v129, v76, v2, v129 op_sel:[1,0,0]
	v_pk_fma_f16 v128, v76, v3, v128 op_sel:[1,0,0]
	v_pk_fma_f16 v127, v76, v4, v127 op_sel:[1,0,0]
	v_pk_fma_f16 v125, v76, v5, v125 op_sel:[1,0,0]
	v_pk_fma_f16 v123, v76, v6, v123 op_sel:[1,0,0]
	v_pk_fma_f16 v121, v76, v7, v121 op_sel:[1,0,0]
	v_pk_fma_f16 v136, v76, v8, v136 op_sel:[1,0,0]
	v_pk_fma_f16 v135, v76, v9, v135 op_sel:[1,0,0]
	v_pk_fma_f16 v134, v76, v10, v134 op_sel:[1,0,0]
	v_pk_fma_f16 v132, v76, v11, v132 op_sel:[1,0,0]
	v_pk_fma_f16 v130, v76, v12, v130 op_sel:[1,0,0]
	v_pk_fma_f16 v126, v76, v13, v126 op_sel:[1,0,0]
	v_pk_fma_f16 v124, v76, v14, v124 op_sel:[1,0,0]
	v_pk_fma_f16 v122, v76, v15, v122 op_sel:[1,0,0]
	s_waitcnt vmcnt(30)
	v_cvt_scalef32_pk32_f16_fp6 v[0:15], v[216:221], 1.0
	v_and_b32_e32 v216, 0xffff, v225
	v_mad_u32_u24 v220, v216, s22, v117
	v_mad_u32_u24 v216, v216, s22, v116
	global_load_dwordx4 v[216:219], v216, s[2:3]
	global_load_dwordx2 v[220:221], v220, s[2:3]
	v_pk_fma_f16 v133, v77, v0, v133 op_sel:[1,0,0]
	v_pk_fma_f16 v131, v77, v1, v131 op_sel:[1,0,0]
	v_pk_fma_f16 v129, v77, v2, v129 op_sel:[1,0,0]
	v_pk_fma_f16 v128, v77, v3, v128 op_sel:[1,0,0]
	v_pk_fma_f16 v127, v77, v4, v127 op_sel:[1,0,0]
	v_pk_fma_f16 v125, v77, v5, v125 op_sel:[1,0,0]
	v_pk_fma_f16 v123, v77, v6, v123 op_sel:[1,0,0]
	v_pk_fma_f16 v121, v77, v7, v121 op_sel:[1,0,0]
	v_pk_fma_f16 v136, v77, v8, v136 op_sel:[1,0,0]
	v_pk_fma_f16 v135, v77, v9, v135 op_sel:[1,0,0]
	v_pk_fma_f16 v134, v77, v10, v134 op_sel:[1,0,0]
	v_pk_fma_f16 v132, v77, v11, v132 op_sel:[1,0,0]
	v_pk_fma_f16 v130, v77, v12, v130 op_sel:[1,0,0]
	v_pk_fma_f16 v126, v77, v13, v126 op_sel:[1,0,0]
	v_pk_fma_f16 v124, v77, v14, v124 op_sel:[1,0,0]
	v_pk_fma_f16 v122, v77, v15, v122 op_sel:[1,0,0]
	s_waitcnt vmcnt(30)
	v_cvt_scalef32_pk32_f16_fp6 v[0:15], v[22:27], 1.0
	v_and_b32_e32 v22, 0xffff, v104
	v_mad_u32_u24 v26, v22, s22, v117
	v_mad_u32_u24 v22, v22, s22, v116
	global_load_dwordx4 v[22:25], v22, s[2:3]
	global_load_dwordx2 v[26:27], v26, s[2:3]
	v_pk_fma_f16 v133, v78, v0, v133 op_sel:[1,0,0]
	v_pk_fma_f16 v131, v78, v1, v131 op_sel:[1,0,0]
	v_pk_fma_f16 v129, v78, v2, v129 op_sel:[1,0,0]
	v_pk_fma_f16 v128, v78, v3, v128 op_sel:[1,0,0]
	v_pk_fma_f16 v127, v78, v4, v127 op_sel:[1,0,0]
	v_pk_fma_f16 v125, v78, v5, v125 op_sel:[1,0,0]
	v_pk_fma_f16 v123, v78, v6, v123 op_sel:[1,0,0]
	v_pk_fma_f16 v121, v78, v7, v121 op_sel:[1,0,0]
	v_pk_fma_f16 v136, v78, v8, v136 op_sel:[1,0,0]
	v_pk_fma_f16 v135, v78, v9, v135 op_sel:[1,0,0]
	v_pk_fma_f16 v134, v78, v10, v134 op_sel:[1,0,0]
	v_pk_fma_f16 v132, v78, v11, v132 op_sel:[1,0,0]
	v_pk_fma_f16 v130, v78, v12, v130 op_sel:[1,0,0]
	v_pk_fma_f16 v126, v78, v13, v126 op_sel:[1,0,0]
	v_pk_fma_f16 v124, v78, v14, v124 op_sel:[1,0,0]
	v_pk_fma_f16 v122, v78, v15, v122 op_sel:[1,0,0]
	s_waitcnt vmcnt(30)
	v_cvt_scalef32_pk32_f16_fp6 v[0:15], v[16:21], 1.0
	v_and_b32_e32 v16, 0xffff, v105
	v_mad_u32_u24 v20, v16, s22, v117
	v_mad_u32_u24 v16, v16, s22, v116
	global_load_dwordx4 v[16:19], v16, s[2:3]
	global_load_dwordx2 v[20:21], v20, s[2:3]
	v_pk_fma_f16 v133, v79, v0, v133 op_sel:[1,0,0]
	v_pk_fma_f16 v131, v79, v1, v131 op_sel:[1,0,0]
	v_pk_fma_f16 v129, v79, v2, v129 op_sel:[1,0,0]
	v_pk_fma_f16 v128, v79, v3, v128 op_sel:[1,0,0]
	v_pk_fma_f16 v127, v79, v4, v127 op_sel:[1,0,0]
	v_pk_fma_f16 v125, v79, v5, v125 op_sel:[1,0,0]
	v_pk_fma_f16 v123, v79, v6, v123 op_sel:[1,0,0]
	v_pk_fma_f16 v121, v79, v7, v121 op_sel:[1,0,0]
	v_pk_fma_f16 v136, v79, v8, v136 op_sel:[1,0,0]
	v_pk_fma_f16 v135, v79, v9, v135 op_sel:[1,0,0]
	v_pk_fma_f16 v134, v79, v10, v134 op_sel:[1,0,0]
	v_pk_fma_f16 v132, v79, v11, v132 op_sel:[1,0,0]
	v_pk_fma_f16 v130, v79, v12, v130 op_sel:[1,0,0]
	v_pk_fma_f16 v126, v79, v13, v126 op_sel:[1,0,0]
	v_pk_fma_f16 v124, v79, v14, v124 op_sel:[1,0,0]
	v_pk_fma_f16 v122, v79, v15, v122 op_sel:[1,0,0]
	s_waitcnt vmcnt(30)
	v_cvt_scalef32_pk32_f16_fp6 v[0:15], v[138:143], 1.0
	v_pk_fma_f16 v133, v242, v0, v133 op_sel:[1,0,0]
	v_pk_fma_f16 v131, v242, v1, v131 op_sel:[1,0,0]
	v_pk_fma_f16 v129, v242, v2, v129 op_sel:[1,0,0]
	v_pk_fma_f16 v128, v242, v3, v128 op_sel:[1,0,0]
	v_pk_fma_f16 v127, v242, v4, v127 op_sel:[1,0,0]
	v_pk_fma_f16 v125, v242, v5, v125 op_sel:[1,0,0]
	v_pk_fma_f16 v123, v242, v6, v123 op_sel:[1,0,0]
	v_pk_fma_f16 v121, v242, v7, v121 op_sel:[1,0,0]
	v_pk_fma_f16 v136, v242, v8, v136 op_sel:[1,0,0]
	v_pk_fma_f16 v135, v242, v9, v135 op_sel:[1,0,0]
	v_pk_fma_f16 v134, v242, v10, v134 op_sel:[1,0,0]
	v_pk_fma_f16 v132, v242, v11, v132 op_sel:[1,0,0]
	v_pk_fma_f16 v130, v242, v12, v130 op_sel:[1,0,0]
	v_pk_fma_f16 v126, v242, v13, v126 op_sel:[1,0,0]
	v_pk_fma_f16 v124, v242, v14, v124 op_sel:[1,0,0]
	v_pk_fma_f16 v122, v242, v15, v122 op_sel:[1,0,0]
	s_waitcnt vmcnt(28)
	v_cvt_scalef32_pk32_f16_fp6 v[0:15], v[144:149], 1.0
	v_pk_fma_f16 v133, v243, v0, v133 op_sel:[1,0,0]
	v_pk_fma_f16 v131, v243, v1, v131 op_sel:[1,0,0]
	v_pk_fma_f16 v129, v243, v2, v129 op_sel:[1,0,0]
	v_pk_fma_f16 v128, v243, v3, v128 op_sel:[1,0,0]
	v_pk_fma_f16 v127, v243, v4, v127 op_sel:[1,0,0]
	v_pk_fma_f16 v125, v243, v5, v125 op_sel:[1,0,0]
	v_pk_fma_f16 v123, v243, v6, v123 op_sel:[1,0,0]
	v_pk_fma_f16 v121, v243, v7, v121 op_sel:[1,0,0]
	v_pk_fma_f16 v136, v243, v8, v136 op_sel:[1,0,0]
	v_pk_fma_f16 v135, v243, v9, v135 op_sel:[1,0,0]
	v_pk_fma_f16 v134, v243, v10, v134 op_sel:[1,0,0]
	v_pk_fma_f16 v132, v243, v11, v132 op_sel:[1,0,0]
	v_pk_fma_f16 v130, v243, v12, v130 op_sel:[1,0,0]
	v_pk_fma_f16 v126, v243, v13, v126 op_sel:[1,0,0]
	v_pk_fma_f16 v124, v243, v14, v124 op_sel:[1,0,0]
	v_pk_fma_f16 v122, v243, v15, v122 op_sel:[1,0,0]
	s_waitcnt vmcnt(26)
	v_cvt_scalef32_pk32_f16_fp6 v[0:15], v[150:155], 1.0
	v_pk_fma_f16 v133, v244, v0, v133 op_sel:[1,0,0]
	v_pk_fma_f16 v131, v244, v1, v131 op_sel:[1,0,0]
	v_pk_fma_f16 v129, v244, v2, v129 op_sel:[1,0,0]
	v_pk_fma_f16 v128, v244, v3, v128 op_sel:[1,0,0]
	v_pk_fma_f16 v127, v244, v4, v127 op_sel:[1,0,0]
	v_pk_fma_f16 v125, v244, v5, v125 op_sel:[1,0,0]
	v_pk_fma_f16 v123, v244, v6, v123 op_sel:[1,0,0]
	v_pk_fma_f16 v121, v244, v7, v121 op_sel:[1,0,0]
	v_pk_fma_f16 v136, v244, v8, v136 op_sel:[1,0,0]
	v_pk_fma_f16 v135, v244, v9, v135 op_sel:[1,0,0]
	v_pk_fma_f16 v134, v244, v10, v134 op_sel:[1,0,0]
	v_pk_fma_f16 v132, v244, v11, v132 op_sel:[1,0,0]
	v_pk_fma_f16 v130, v244, v12, v130 op_sel:[1,0,0]
	v_pk_fma_f16 v126, v244, v13, v126 op_sel:[1,0,0]
	v_pk_fma_f16 v124, v244, v14, v124 op_sel:[1,0,0]
	v_pk_fma_f16 v122, v244, v15, v122 op_sel:[1,0,0]
	s_waitcnt vmcnt(24)
	v_cvt_scalef32_pk32_f16_fp6 v[0:15], v[156:161], 1.0
	v_pk_fma_f16 v133, v245, v0, v133 op_sel:[1,0,0]
	v_pk_fma_f16 v131, v245, v1, v131 op_sel:[1,0,0]
	v_pk_fma_f16 v129, v245, v2, v129 op_sel:[1,0,0]
	v_pk_fma_f16 v128, v245, v3, v128 op_sel:[1,0,0]
	v_pk_fma_f16 v127, v245, v4, v127 op_sel:[1,0,0]
	v_pk_fma_f16 v125, v245, v5, v125 op_sel:[1,0,0]
	v_pk_fma_f16 v123, v245, v6, v123 op_sel:[1,0,0]
	v_pk_fma_f16 v121, v245, v7, v121 op_sel:[1,0,0]
	v_pk_fma_f16 v136, v245, v8, v136 op_sel:[1,0,0]
	v_pk_fma_f16 v135, v245, v9, v135 op_sel:[1,0,0]
	v_pk_fma_f16 v134, v245, v10, v134 op_sel:[1,0,0]
	v_pk_fma_f16 v132, v245, v11, v132 op_sel:[1,0,0]
	v_pk_fma_f16 v130, v245, v12, v130 op_sel:[1,0,0]
	v_pk_fma_f16 v126, v245, v13, v126 op_sel:[1,0,0]
	v_pk_fma_f16 v124, v245, v14, v124 op_sel:[1,0,0]
	v_pk_fma_f16 v122, v245, v15, v122 op_sel:[1,0,0]
	s_waitcnt vmcnt(22)
	v_cvt_scalef32_pk32_f16_fp6 v[0:15], v[162:167], 1.0
	v_pk_fma_f16 v133, v246, v0, v133 op_sel:[1,0,0]
	v_pk_fma_f16 v131, v246, v1, v131 op_sel:[1,0,0]
	v_pk_fma_f16 v129, v246, v2, v129 op_sel:[1,0,0]
	v_pk_fma_f16 v128, v246, v3, v128 op_sel:[1,0,0]
	v_pk_fma_f16 v127, v246, v4, v127 op_sel:[1,0,0]
	v_pk_fma_f16 v125, v246, v5, v125 op_sel:[1,0,0]
	v_pk_fma_f16 v123, v246, v6, v123 op_sel:[1,0,0]
	v_pk_fma_f16 v121, v246, v7, v121 op_sel:[1,0,0]
	v_pk_fma_f16 v136, v246, v8, v136 op_sel:[1,0,0]
	v_pk_fma_f16 v135, v246, v9, v135 op_sel:[1,0,0]
	v_pk_fma_f16 v134, v246, v10, v134 op_sel:[1,0,0]
	v_pk_fma_f16 v132, v246, v11, v132 op_sel:[1,0,0]
	v_pk_fma_f16 v130, v246, v12, v130 op_sel:[1,0,0]
	v_pk_fma_f16 v126, v246, v13, v126 op_sel:[1,0,0]
	v_pk_fma_f16 v124, v246, v14, v124 op_sel:[1,0,0]
	v_pk_fma_f16 v122, v246, v15, v122 op_sel:[1,0,0]
	s_waitcnt vmcnt(20)
	v_cvt_scalef32_pk32_f16_fp6 v[0:15], v[168:173], 1.0
	v_pk_fma_f16 v133, v247, v0, v133 op_sel:[1,0,0]
	v_pk_fma_f16 v131, v247, v1, v131 op_sel:[1,0,0]
	v_pk_fma_f16 v129, v247, v2, v129 op_sel:[1,0,0]
	v_pk_fma_f16 v128, v247, v3, v128 op_sel:[1,0,0]
	v_pk_fma_f16 v127, v247, v4, v127 op_sel:[1,0,0]
	v_pk_fma_f16 v125, v247, v5, v125 op_sel:[1,0,0]
	v_pk_fma_f16 v123, v247, v6, v123 op_sel:[1,0,0]
	v_pk_fma_f16 v121, v247, v7, v121 op_sel:[1,0,0]
	v_pk_fma_f16 v136, v247, v8, v136 op_sel:[1,0,0]
	v_pk_fma_f16 v135, v247, v9, v135 op_sel:[1,0,0]
	v_pk_fma_f16 v134, v247, v10, v134 op_sel:[1,0,0]
	v_pk_fma_f16 v132, v247, v11, v132 op_sel:[1,0,0]
	v_pk_fma_f16 v130, v247, v12, v130 op_sel:[1,0,0]
	v_pk_fma_f16 v126, v247, v13, v126 op_sel:[1,0,0]
	v_pk_fma_f16 v124, v247, v14, v124 op_sel:[1,0,0]
	v_pk_fma_f16 v122, v247, v15, v122 op_sel:[1,0,0]
	s_waitcnt vmcnt(18)
	v_cvt_scalef32_pk32_f16_fp6 v[0:15], v[174:179], 1.0
	v_pk_fma_f16 v133, v248, v0, v133 op_sel:[1,0,0]
	v_pk_fma_f16 v131, v248, v1, v131 op_sel:[1,0,0]
	v_pk_fma_f16 v129, v248, v2, v129 op_sel:[1,0,0]
	v_pk_fma_f16 v128, v248, v3, v128 op_sel:[1,0,0]
	v_pk_fma_f16 v127, v248, v4, v127 op_sel:[1,0,0]
	v_pk_fma_f16 v125, v248, v5, v125 op_sel:[1,0,0]
	v_pk_fma_f16 v123, v248, v6, v123 op_sel:[1,0,0]
	v_pk_fma_f16 v121, v248, v7, v121 op_sel:[1,0,0]
	v_pk_fma_f16 v136, v248, v8, v136 op_sel:[1,0,0]
	v_pk_fma_f16 v135, v248, v9, v135 op_sel:[1,0,0]
	v_pk_fma_f16 v134, v248, v10, v134 op_sel:[1,0,0]
	v_pk_fma_f16 v132, v248, v11, v132 op_sel:[1,0,0]
	v_pk_fma_f16 v130, v248, v12, v130 op_sel:[1,0,0]
	v_pk_fma_f16 v126, v248, v13, v126 op_sel:[1,0,0]
	v_pk_fma_f16 v124, v248, v14, v124 op_sel:[1,0,0]
	v_pk_fma_f16 v122, v248, v15, v122 op_sel:[1,0,0]
	s_waitcnt vmcnt(16)
	v_cvt_scalef32_pk32_f16_fp6 v[0:15], v[180:185], 1.0
	v_pk_fma_f16 v133, v249, v0, v133 op_sel:[1,0,0]
	v_pk_fma_f16 v131, v249, v1, v131 op_sel:[1,0,0]
	v_pk_fma_f16 v129, v249, v2, v129 op_sel:[1,0,0]
	v_pk_fma_f16 v128, v249, v3, v128 op_sel:[1,0,0]
	v_pk_fma_f16 v127, v249, v4, v127 op_sel:[1,0,0]
	v_pk_fma_f16 v125, v249, v5, v125 op_sel:[1,0,0]
	v_pk_fma_f16 v123, v249, v6, v123 op_sel:[1,0,0]
	v_pk_fma_f16 v121, v249, v7, v121 op_sel:[1,0,0]
	v_pk_fma_f16 v136, v249, v8, v136 op_sel:[1,0,0]
	v_pk_fma_f16 v135, v249, v9, v135 op_sel:[1,0,0]
	v_pk_fma_f16 v134, v249, v10, v134 op_sel:[1,0,0]
	v_pk_fma_f16 v132, v249, v11, v132 op_sel:[1,0,0]
	v_pk_fma_f16 v130, v249, v12, v130 op_sel:[1,0,0]
	v_pk_fma_f16 v126, v249, v13, v126 op_sel:[1,0,0]
	v_pk_fma_f16 v124, v249, v14, v124 op_sel:[1,0,0]
	v_pk_fma_f16 v122, v249, v15, v122 op_sel:[1,0,0]
	s_waitcnt vmcnt(14)
	v_cvt_scalef32_pk32_f16_fp6 v[0:15], v[186:191], 1.0
	v_pk_fma_f16 v133, v238, v0, v133 op_sel:[1,0,0]
	v_pk_fma_f16 v131, v238, v1, v131 op_sel:[1,0,0]
	v_pk_fma_f16 v129, v238, v2, v129 op_sel:[1,0,0]
	v_pk_fma_f16 v128, v238, v3, v128 op_sel:[1,0,0]
	v_pk_fma_f16 v127, v238, v4, v127 op_sel:[1,0,0]
	v_pk_fma_f16 v125, v238, v5, v125 op_sel:[1,0,0]
	v_pk_fma_f16 v123, v238, v6, v123 op_sel:[1,0,0]
	v_pk_fma_f16 v121, v238, v7, v121 op_sel:[1,0,0]
	v_pk_fma_f16 v136, v238, v8, v136 op_sel:[1,0,0]
	v_pk_fma_f16 v135, v238, v9, v135 op_sel:[1,0,0]
	v_pk_fma_f16 v134, v238, v10, v134 op_sel:[1,0,0]
	v_pk_fma_f16 v132, v238, v11, v132 op_sel:[1,0,0]
	v_pk_fma_f16 v130, v238, v12, v130 op_sel:[1,0,0]
	v_pk_fma_f16 v126, v238, v13, v126 op_sel:[1,0,0]
	v_pk_fma_f16 v124, v238, v14, v124 op_sel:[1,0,0]
	v_pk_fma_f16 v122, v238, v15, v122 op_sel:[1,0,0]
	s_waitcnt vmcnt(12)
	v_cvt_scalef32_pk32_f16_fp6 v[0:15], v[192:197], 1.0
	v_pk_fma_f16 v133, v239, v0, v133 op_sel:[1,0,0]
	v_pk_fma_f16 v131, v239, v1, v131 op_sel:[1,0,0]
	v_pk_fma_f16 v129, v239, v2, v129 op_sel:[1,0,0]
	v_pk_fma_f16 v128, v239, v3, v128 op_sel:[1,0,0]
	v_pk_fma_f16 v127, v239, v4, v127 op_sel:[1,0,0]
	v_pk_fma_f16 v125, v239, v5, v125 op_sel:[1,0,0]
	v_pk_fma_f16 v123, v239, v6, v123 op_sel:[1,0,0]
	v_pk_fma_f16 v121, v239, v7, v121 op_sel:[1,0,0]
	v_pk_fma_f16 v136, v239, v8, v136 op_sel:[1,0,0]
	v_pk_fma_f16 v135, v239, v9, v135 op_sel:[1,0,0]
	v_pk_fma_f16 v134, v239, v10, v134 op_sel:[1,0,0]
	v_pk_fma_f16 v132, v239, v11, v132 op_sel:[1,0,0]
	v_pk_fma_f16 v130, v239, v12, v130 op_sel:[1,0,0]
	v_pk_fma_f16 v126, v239, v13, v126 op_sel:[1,0,0]
	v_pk_fma_f16 v124, v239, v14, v124 op_sel:[1,0,0]
	v_pk_fma_f16 v122, v239, v15, v122 op_sel:[1,0,0]
	s_waitcnt vmcnt(10)
	v_cvt_scalef32_pk32_f16_fp6 v[0:15], v[198:203], 1.0
	v_pk_fma_f16 v133, v240, v0, v133 op_sel:[1,0,0]
	v_pk_fma_f16 v131, v240, v1, v131 op_sel:[1,0,0]
	v_pk_fma_f16 v129, v240, v2, v129 op_sel:[1,0,0]
	v_pk_fma_f16 v128, v240, v3, v128 op_sel:[1,0,0]
	v_pk_fma_f16 v127, v240, v4, v127 op_sel:[1,0,0]
	v_pk_fma_f16 v125, v240, v5, v125 op_sel:[1,0,0]
	v_pk_fma_f16 v123, v240, v6, v123 op_sel:[1,0,0]
	v_pk_fma_f16 v121, v240, v7, v121 op_sel:[1,0,0]
	v_pk_fma_f16 v136, v240, v8, v136 op_sel:[1,0,0]
	v_pk_fma_f16 v135, v240, v9, v135 op_sel:[1,0,0]
	v_pk_fma_f16 v134, v240, v10, v134 op_sel:[1,0,0]
	v_pk_fma_f16 v132, v240, v11, v132 op_sel:[1,0,0]
	v_pk_fma_f16 v130, v240, v12, v130 op_sel:[1,0,0]
	v_pk_fma_f16 v126, v240, v13, v126 op_sel:[1,0,0]
	v_pk_fma_f16 v124, v240, v14, v124 op_sel:[1,0,0]
	v_pk_fma_f16 v122, v240, v15, v122 op_sel:[1,0,0]
	s_waitcnt vmcnt(8)
	v_cvt_scalef32_pk32_f16_fp6 v[0:15], v[204:209], 1.0
	v_pk_fma_f16 v133, v241, v0, v133 op_sel:[1,0,0]
	v_pk_fma_f16 v131, v241, v1, v131 op_sel:[1,0,0]
	v_pk_fma_f16 v129, v241, v2, v129 op_sel:[1,0,0]
	v_pk_fma_f16 v128, v241, v3, v128 op_sel:[1,0,0]
	v_pk_fma_f16 v127, v241, v4, v127 op_sel:[1,0,0]
	v_pk_fma_f16 v125, v241, v5, v125 op_sel:[1,0,0]
	v_pk_fma_f16 v123, v241, v6, v123 op_sel:[1,0,0]
	v_pk_fma_f16 v121, v241, v7, v121 op_sel:[1,0,0]
	v_pk_fma_f16 v136, v241, v8, v136 op_sel:[1,0,0]
	v_pk_fma_f16 v135, v241, v9, v135 op_sel:[1,0,0]
	v_pk_fma_f16 v134, v241, v10, v134 op_sel:[1,0,0]
	v_pk_fma_f16 v132, v241, v11, v132 op_sel:[1,0,0]
	v_pk_fma_f16 v130, v241, v12, v130 op_sel:[1,0,0]
	v_pk_fma_f16 v126, v241, v13, v126 op_sel:[1,0,0]
	v_pk_fma_f16 v124, v241, v14, v124 op_sel:[1,0,0]
	v_pk_fma_f16 v122, v241, v15, v122 op_sel:[1,0,0]
	s_waitcnt vmcnt(6)
	v_cvt_scalef32_pk32_f16_fp6 v[0:15], v[210:215], 1.0
	v_pk_fma_f16 v133, v224, v0, v133 op_sel:[1,0,0]
	v_pk_fma_f16 v131, v224, v1, v131 op_sel:[1,0,0]
	v_pk_fma_f16 v129, v224, v2, v129 op_sel:[1,0,0]
	v_pk_fma_f16 v128, v224, v3, v128 op_sel:[1,0,0]
	v_pk_fma_f16 v127, v224, v4, v127 op_sel:[1,0,0]
	v_pk_fma_f16 v125, v224, v5, v125 op_sel:[1,0,0]
	v_pk_fma_f16 v123, v224, v6, v123 op_sel:[1,0,0]
	v_pk_fma_f16 v121, v224, v7, v121 op_sel:[1,0,0]
	v_pk_fma_f16 v136, v224, v8, v136 op_sel:[1,0,0]
	v_pk_fma_f16 v135, v224, v9, v135 op_sel:[1,0,0]
	v_pk_fma_f16 v134, v224, v10, v134 op_sel:[1,0,0]
	v_pk_fma_f16 v132, v224, v11, v132 op_sel:[1,0,0]
	v_pk_fma_f16 v130, v224, v12, v130 op_sel:[1,0,0]
	v_pk_fma_f16 v126, v224, v13, v126 op_sel:[1,0,0]
	v_pk_fma_f16 v124, v224, v14, v124 op_sel:[1,0,0]
	v_pk_fma_f16 v122, v224, v15, v122 op_sel:[1,0,0]
	s_waitcnt vmcnt(4)
	v_cvt_scalef32_pk32_f16_fp6 v[0:15], v[216:221], 1.0
	v_pk_fma_f16 v133, v225, v0, v133 op_sel:[1,0,0]
	v_pk_fma_f16 v131, v225, v1, v131 op_sel:[1,0,0]
	v_pk_fma_f16 v129, v225, v2, v129 op_sel:[1,0,0]
	v_pk_fma_f16 v128, v225, v3, v128 op_sel:[1,0,0]
	v_pk_fma_f16 v127, v225, v4, v127 op_sel:[1,0,0]
	v_pk_fma_f16 v125, v225, v5, v125 op_sel:[1,0,0]
	v_pk_fma_f16 v123, v225, v6, v123 op_sel:[1,0,0]
	v_pk_fma_f16 v121, v225, v7, v121 op_sel:[1,0,0]
	v_pk_fma_f16 v136, v225, v8, v136 op_sel:[1,0,0]
	v_pk_fma_f16 v135, v225, v9, v135 op_sel:[1,0,0]
	v_pk_fma_f16 v134, v225, v10, v134 op_sel:[1,0,0]
	v_pk_fma_f16 v132, v225, v11, v132 op_sel:[1,0,0]
	v_pk_fma_f16 v130, v225, v12, v130 op_sel:[1,0,0]
	v_pk_fma_f16 v126, v225, v13, v126 op_sel:[1,0,0]
	v_pk_fma_f16 v124, v225, v14, v124 op_sel:[1,0,0]
	v_pk_fma_f16 v122, v225, v15, v122 op_sel:[1,0,0]
	s_waitcnt vmcnt(2)
	v_cvt_scalef32_pk32_f16_fp6 v[0:15], v[22:27], 1.0
	v_pk_fma_f16 v133, v104, v0, v133 op_sel:[1,0,0]
	v_pk_fma_f16 v131, v104, v1, v131 op_sel:[1,0,0]
	v_pk_fma_f16 v129, v104, v2, v129 op_sel:[1,0,0]
	v_pk_fma_f16 v128, v104, v3, v128 op_sel:[1,0,0]
	v_pk_fma_f16 v127, v104, v4, v127 op_sel:[1,0,0]
	v_pk_fma_f16 v125, v104, v5, v125 op_sel:[1,0,0]
	v_pk_fma_f16 v123, v104, v6, v123 op_sel:[1,0,0]
	v_pk_fma_f16 v121, v104, v7, v121 op_sel:[1,0,0]
	v_pk_fma_f16 v136, v104, v8, v136 op_sel:[1,0,0]
	v_pk_fma_f16 v135, v104, v9, v135 op_sel:[1,0,0]
	v_pk_fma_f16 v134, v104, v10, v134 op_sel:[1,0,0]
	v_pk_fma_f16 v132, v104, v11, v132 op_sel:[1,0,0]
	v_pk_fma_f16 v130, v104, v12, v130 op_sel:[1,0,0]
	v_pk_fma_f16 v126, v104, v13, v126 op_sel:[1,0,0]
	v_pk_fma_f16 v124, v104, v14, v124 op_sel:[1,0,0]
	v_pk_fma_f16 v122, v104, v15, v122 op_sel:[1,0,0]
	s_waitcnt vmcnt(0)
	v_cvt_scalef32_pk32_f16_fp6 v[0:15], v[16:21], 1.0
	v_pk_fma_f16 v133, v105, v0, v133 op_sel:[1,0,0]
	v_pk_fma_f16 v131, v105, v1, v131 op_sel:[1,0,0]
	v_pk_fma_f16 v129, v105, v2, v129 op_sel:[1,0,0]
	v_pk_fma_f16 v128, v105, v3, v128 op_sel:[1,0,0]
	v_pk_fma_f16 v127, v105, v4, v127 op_sel:[1,0,0]
	v_pk_fma_f16 v125, v105, v5, v125 op_sel:[1,0,0]
	v_pk_fma_f16 v123, v105, v6, v123 op_sel:[1,0,0]
	v_pk_fma_f16 v121, v105, v7, v121 op_sel:[1,0,0]
	v_pk_fma_f16 v136, v105, v8, v136 op_sel:[1,0,0]
	v_pk_fma_f16 v135, v105, v9, v135 op_sel:[1,0,0]
	v_pk_fma_f16 v134, v105, v10, v134 op_sel:[1,0,0]
	v_pk_fma_f16 v132, v105, v11, v132 op_sel:[1,0,0]
	v_pk_fma_f16 v130, v105, v12, v130 op_sel:[1,0,0]
	v_pk_fma_f16 v126, v105, v13, v126 op_sel:[1,0,0]
	v_pk_fma_f16 v124, v105, v14, v124 op_sel:[1,0,0]
	v_pk_fma_f16 v122, v105, v15, v122 op_sel:[1,0,0]
	s_cmp_eq_u32 s43, 0
	s_cbranch_scc1 .Lg2_save
	s_setprio 0
	global_load_dword v82, v95, s[4:5]
	v_permlane32_swap_b32_e32 v133, v136
	v_permlane32_swap_b32_e32 v131, v135
	v_permlane32_swap_b32_e32 v129, v134
	v_cvt_f32_f16_e32 v14, v133
	v_cvt_f32_f16_sdwa v15, v133 dst_sel:DWORD dst_unused:UNUSED_PAD src0_sel:WORD_1
	v_cvt_f32_f16_e32 v16, v136
	v_cvt_f32_f16_sdwa v17, v136 dst_sel:DWORD dst_unused:UNUSED_PAD src0_sel:WORD_1
	v_cvt_f32_f16_e32 v18, v131
	v_cvt_f32_f16_sdwa v19, v131 dst_sel:DWORD dst_unused:UNUSED_PAD src0_sel:WORD_1
	v_cvt_f32_f16_e32 v20, v135
	v_cvt_f32_f16_sdwa v21, v135 dst_sel:DWORD dst_unused:UNUSED_PAD src0_sel:WORD_1
	v_cvt_f32_f16_e32 v22, v129
	v_cvt_f32_f16_sdwa v23, v129 dst_sel:DWORD dst_unused:UNUSED_PAD src0_sel:WORD_1
	v_cvt_f32_f16_e32 v24, v134
	v_cvt_f32_f16_sdwa v25, v134 dst_sel:DWORD dst_unused:UNUSED_PAD src0_sel:WORD_1
	v_permlane32_swap_b32_e32 v128, v132
	v_cvt_f32_f16_sdwa v7, v113 dst_sel:DWORD dst_unused:UNUSED_PAD src0_sel:WORD_1
	v_cvt_f32_f16_e32 v6, v113
	v_cvt_f32_f16_sdwa v9, v110 dst_sel:DWORD dst_unused:UNUSED_PAD src0_sel:WORD_1
	v_cvt_f32_f16_e32 v8, v110
	v_cvt_f32_f16_e32 v26, v128
	v_cvt_f32_f16_sdwa v27, v128 dst_sel:DWORD dst_unused:UNUSED_PAD src0_sel:WORD_1
	v_cvt_f32_f16_e32 v76, v132
	v_cvt_f32_f16_sdwa v77, v132 dst_sel:DWORD dst_unused:UNUSED_PAD src0_sel:WORD_1
	v_pk_add_f32 v[14:15], v[14:15], v[16:17]
	v_pk_add_f32 v[16:17], v[18:19], v[20:21]
	v_pk_add_f32 v[18:19], v[22:23], v[24:25]
	v_pk_mul_f32 v[16:17], v[16:17], s[16:17] op_sel_hi:[1,0]
	v_pk_mul_f32 v[18:19], v[18:19], s[16:17] op_sel_hi:[1,0]
	v_permlane32_swap_b32_e32 v125, v126
	v_cvt_f32_f16_sdwa v11, v111 dst_sel:DWORD dst_unused:UNUSED_PAD src0_sel:WORD_1
	v_cvt_f32_f16_e32 v10, v111
	v_pk_mul_f32 v[16:17], v[70:71], v[16:17]
	v_pk_mul_f32 v[18:19], v[72:73], v[18:19]
	v_pk_add_f32 v[20:21], v[26:27], v[76:77]
	v_pk_fma_f32 v[6:7], v[6:7], s[18:19], v[16:17] op_sel_hi:[1,0,1]
	v_pk_fma_f32 v[8:9], v[8:9], s[18:19], v[18:19] op_sel_hi:[1,0,1]
	v_cvt_f32_f16_e32 v16, v125
	v_cvt_f32_f16_sdwa v17, v125 dst_sel:DWORD dst_unused:UNUSED_PAD src0_sel:WORD_1
	v_cvt_f32_f16_e32 v18, v126
	v_cvt_f32_f16_sdwa v19, v126 dst_sel:DWORD dst_unused:UNUSED_PAD src0_sel:WORD_1
	v_pk_mul_f32 v[20:21], v[20:21], s[16:17] op_sel_hi:[1,0]
	v_permlane32_swap_b32_e32 v127, v130
	v_pk_mul_f32 v[20:21], v[74:75], v[20:21]
	v_cvt_f32_f16_sdwa v5, v112 dst_sel:DWORD dst_unused:UNUSED_PAD src0_sel:WORD_1
	v_cvt_f32_f16_e32 v4, v112
	v_cvt_f32_f16_e32 v78, v127
	v_cvt_f32_f16_sdwa v79, v127 dst_sel:DWORD dst_unused:UNUSED_PAD src0_sel:WORD_1
	v_cvt_f32_f16_e32 v80, v130
	v_cvt_f32_f16_sdwa v81, v130 dst_sel:DWORD dst_unused:UNUSED_PAD src0_sel:WORD_1
	v_pk_fma_f32 v[10:11], v[10:11], s[18:19], v[20:21] op_sel_hi:[1,0,1]
	v_cvt_f32_f16_sdwa v21, v109 dst_sel:DWORD dst_unused:UNUSED_PAD src0_sel:WORD_1
	v_cvt_f32_f16_e32 v20, v109
	v_pk_add_f32 v[16:17], v[16:17], v[18:19]
	v_pk_mul_f32 v[14:15], v[14:15], s[16:17] op_sel_hi:[1,0]
	v_pk_mul_f32 v[16:17], v[16:17], s[16:17] op_sel_hi:[1,0]
	v_permlane32_swap_b32_e32 v123, v124
	v_lshlrev_b64 v[2:3], 12, v[94:95]
	v_cvt_f32_f16_sdwa v13, v108 dst_sel:DWORD dst_unused:UNUSED_PAD src0_sel:WORD_1
	v_cvt_f32_f16_e32 v12, v108
	v_pk_mul_f32 v[14:15], v[68:69], v[14:15]
	v_pk_mul_f32 v[16:17], v[66:67], v[16:17]
	v_lshl_add_u64 v[0:1], v[114:115], 2, s[8:9]
	v_lshl_add_u64 v[2:3], s[6:7], 0, v[2:3]
	v_pk_add_f32 v[22:23], v[78:79], v[80:81]
	v_pk_fma_f32 v[4:5], v[4:5], s[18:19], v[14:15] op_sel_hi:[1,0,1]
	v_pk_fma_f32 v[16:17], v[20:21], s[18:19], v[16:17] op_sel_hi:[1,0,1]
	v_cvt_f32_f16_e32 v18, v123
	v_cvt_f32_f16_sdwa v19, v123 dst_sel:DWORD dst_unused:UNUSED_PAD src0_sel:WORD_1
	v_cvt_f32_f16_e32 v20, v124
	v_cvt_f32_f16_sdwa v21, v124 dst_sel:DWORD dst_unused:UNUSED_PAD src0_sel:WORD_1
	v_cndmask_b32_e64 v1, v3, v1, s[0:1]
	v_pk_mul_f32 v[22:23], v[22:23], s[16:17] op_sel_hi:[1,0]
	v_add_f32_e32 v3, 0, v4
	v_pk_mul_f32 v[22:23], v[64:65], v[22:23]
	v_add_f32_e32 v3, v5, v3
	v_pk_fma_f32 v[12:13], v[12:13], s[18:19], v[22:23] op_sel_hi:[1,0,1]
	v_add_f32_e32 v3, v6, v3
	v_cvt_f32_f16_sdwa v23, v106 dst_sel:DWORD dst_unused:UNUSED_PAD src0_sel:WORD_1
	v_cvt_f32_f16_e32 v22, v106
	v_add_f32_e32 v3, v7, v3
	v_pk_add_f32 v[18:19], v[18:19], v[20:21]
	v_add_f32_e32 v3, v8, v3
	v_pk_mul_f32 v[18:19], v[18:19], s[16:17] op_sel_hi:[1,0]
	v_permlane32_swap_b32_e32 v121, v122
	v_add_f32_e32 v3, v9, v3
	v_pk_mul_f32 v[18:19], v[60:61], v[18:19]
	v_add_f32_e32 v3, v10, v3
	v_pk_fma_f32 v[18:19], v[22:23], s[18:19], v[18:19] op_sel_hi:[1,0,1]
	v_cvt_f32_f16_e32 v20, v121
	v_cvt_f32_f16_sdwa v21, v121 dst_sel:DWORD dst_unused:UNUSED_PAD src0_sel:WORD_1
	v_cvt_f32_f16_e32 v22, v122
	v_cvt_f32_f16_sdwa v23, v122 dst_sel:DWORD dst_unused:UNUSED_PAD src0_sel:WORD_1
	v_add_f32_e32 v3, v11, v3
	v_add_f32_e32 v3, v12, v3
	v_add_f32_e32 v3, v13, v3
	v_cvt_f32_f16_sdwa v25, v107 dst_sel:DWORD dst_unused:UNUSED_PAD src0_sel:WORD_1
	v_cvt_f32_f16_e32 v24, v107
	v_add_f32_e32 v3, v16, v3
	v_pk_add_f32 v[20:21], v[20:21], v[22:23]
	v_add_f32_e32 v3, v17, v3
	v_pk_mul_f32 v[20:21], v[20:21], s[16:17] op_sel_hi:[1,0]
	v_add_f32_e32 v3, v18, v3
	v_pk_mul_f32 v[20:21], v[62:63], v[20:21]
	v_add_f32_e32 v3, v19, v3
	v_pk_fma_f32 v[20:21], v[24:25], s[18:19], v[20:21] op_sel_hi:[1,0,1]
	s_waitcnt vmcnt(0)
	v_cmp_neq_f32_e32 vcc, 0, v82
	v_add_f32_e32 v3, v20, v3
	v_add_f32_e32 v3, v21, v3
	v_mov_b32_e32 v15, v3
	s_nop 1
	v_permlane32_swap_b32_e32 v3, v15
	v_add_f32_e32 v3, v3, v15
	v_mov_b32_e32 v15, v3
	s_nop 1
	v_permlane16_swap_b32_e32 v3, v15
	v_add_f32_e32 v3, v3, v15
	v_cndmask_b32_e32 v14, 0, v120, vcc
	v_cndmask_b32_e64 v0, v2, v0, s[0:1]
	v_add_f32_dpp v3, v3, v3 row_ror:8 row_mask:0xf bank_mask:0xf bound_ctrl:1
	v_mov_b32_e32 v101, v95
	s_nop 0
	v_add_f32_dpp v3, v3, v3 row_ror:4 row_mask:0xf bank_mask:0xf bound_ctrl:1
	s_nop 1
	v_add_f32_dpp v3, v3, v3 quad_perm:[2,3,0,1] row_mask:0xf bank_mask:0xf bound_ctrl:1
	s_nop 1
	v_add_f32_dpp v3, v3, v3 quad_perm:[1,0,3,2] row_mask:0xf bank_mask:0xf bound_ctrl:1
	v_mul_f32_e32 v22, 0x3a800000, v3
	v_pk_add_f32 v[4:5], v[4:5], v[22:23] op_sel_hi:[1,0] neg_lo:[0,1] neg_hi:[0,1]
	v_pk_add_f32 v[6:7], v[6:7], v[22:23] op_sel_hi:[1,0] neg_lo:[0,1] neg_hi:[0,1]
	v_mul_f32_e32 v24, v5, v5
	v_pk_fma_f32 v[24:25], v[4:5], v[4:5], v[24:25] op_sel_hi:[1,1,0]
	v_mul_f32_e32 v26, v7, v7
	v_pk_fma_f32 v[24:25], v[6:7], v[6:7], v[24:25]
	v_pk_add_f32 v[8:9], v[8:9], v[22:23] op_sel_hi:[1,0] neg_lo:[0,1] neg_hi:[0,1]
	v_pk_add_f32 v[24:25], v[26:27], v[24:25] op_sel_hi:[0,1]
	v_pk_fma_f32 v[24:25], v[8:9], v[8:9], v[24:25]
	v_mul_f32_e32 v26, v9, v9
	v_pk_add_f32 v[24:25], v[26:27], v[24:25] op_sel_hi:[0,1]
	v_pk_add_f32 v[10:11], v[10:11], v[22:23] op_sel_hi:[1,0] neg_lo:[0,1] neg_hi:[0,1]
	v_pk_add_f32 v[12:13], v[12:13], v[22:23] op_sel_hi:[1,0] neg_lo:[0,1] neg_hi:[0,1]
	v_pk_fma_f32 v[24:25], v[10:11], v[10:11], v[24:25]
	v_mul_f32_e32 v26, v11, v11
	v_pk_add_f32 v[24:25], v[26:27], v[24:25] op_sel_hi:[0,1]
	v_pk_fma_f32 v[24:25], v[12:13], v[12:13], v[24:25]
	v_mul_f32_e32 v26, v13, v13
	v_pk_add_f32 v[24:25], v[26:27], v[24:25] op_sel_hi:[0,1]
	v_pk_add_f32 v[16:17], v[16:17], v[22:23] op_sel_hi:[1,0] neg_lo:[0,1] neg_hi:[0,1]
	v_pk_add_f32 v[18:19], v[18:19], v[22:23] op_sel_hi:[1,0] neg_lo:[0,1] neg_hi:[0,1]
	v_pk_fma_f32 v[24:25], v[16:17], v[16:17], v[24:25]
	v_mul_f32_e32 v26, v17, v17
	v_pk_add_f32 v[24:25], v[26:27], v[24:25] op_sel_hi:[0,1]
	v_pk_fma_f32 v[24:25], v[18:19], v[18:19], v[24:25]
	v_mul_f32_e32 v26, v19, v19
	v_pk_add_f32 v[24:25], v[26:27], v[24:25] op_sel_hi:[0,1]
	v_pk_add_f32 v[20:21], v[20:21], v[22:23] op_sel_hi:[1,0] neg_lo:[0,1] neg_hi:[0,1]
	s_nop 0
	v_pk_fma_f32 v[22:23], v[20:21], v[20:21], v[24:25]
	v_mul_f32_e32 v24, v21, v21
	v_pk_add_f32 v[22:23], v[24:25], v[22:23] op_sel_hi:[0,1]
	v_mov_b32_e32 v3, v22
	s_nop 1
	v_permlane32_swap_b32_e32 v22, v3
	v_add_f32_e32 v3, v22, v3
	v_mov_b32_e32 v15, v3
	s_nop 1
	v_permlane16_swap_b32_e32 v3, v15
	v_add_f32_e32 v3, v3, v15
	v_lshl_add_u64 v[22:23], v[0:1], 0, v[100:101]
	s_nop 0
	v_add_f32_dpp v3, v3, v3 row_ror:8 row_mask:0xf bank_mask:0xf bound_ctrl:1
	s_nop 1
	v_add_f32_dpp v3, v3, v3 row_ror:4 row_mask:0xf bank_mask:0xf bound_ctrl:1
	s_nop 1
	v_add_f32_dpp v3, v3, v3 quad_perm:[2,3,0,1] row_mask:0xf bank_mask:0xf bound_ctrl:1
	s_nop 1
	v_add_f32_dpp v3, v3, v3 quad_perm:[1,0,3,2] row_mask:0xf bank_mask:0xf bound_ctrl:1
	v_fmamk_f32 v3, v3, 0x3a800000, v119
	v_mul_f32_e32 v15, 0x4b800000, v3
	v_cmp_gt_f32_e32 vcc, s23, v3
	s_nop 1
	v_cndmask_b32_e32 v3, v3, v15, vcc
	v_rsq_f32_e32 v3, v3
	s_nop 0
	v_mul_f32_e32 v0, 0x45800000, v3
	v_cndmask_b32_e32 v24, v3, v0, vcc
	v_pk_mul_f32 v[0:1], v[6:7], v[24:25] op_sel_hi:[1,0]
	v_pk_mul_f32 v[2:3], v[4:5], v[24:25] op_sel_hi:[1,0]
	v_pk_fma_f32 v[0:1], v[58:59], v[0:1], v[54:55]
	v_pk_fma_f32 v[4:5], v[56:57], v[2:3], v[52:53]
	v_pk_add_f32 v[2:3], v[14:15], v[0:1] op_sel_hi:[0,1]
	v_pk_add_f32 v[0:1], v[14:15], v[4:5] op_sel_hi:[0,1]
	global_store_dwordx4 v[22:23], v[0:3], off
	s_nop 1
	v_pk_mul_f32 v[0:1], v[10:11], v[24:25] op_sel_hi:[1,0]
	v_pk_mul_f32 v[2:3], v[8:9], v[24:25] op_sel_hi:[1,0]
	v_pk_fma_f32 v[0:1], v[50:51], v[0:1], v[46:47]
	v_pk_fma_f32 v[4:5], v[48:49], v[2:3], v[44:45]
	v_pk_add_f32 v[2:3], v[14:15], v[0:1] op_sel_hi:[0,1]
	v_pk_add_f32 v[0:1], v[14:15], v[4:5] op_sel_hi:[0,1]
	global_store_dwordx4 v[22:23], v[0:3], off offset:512
	s_nop 1
	v_pk_mul_f32 v[0:1], v[16:17], v[24:25] op_sel_hi:[1,0]
	v_pk_mul_f32 v[2:3], v[12:13], v[24:25] op_sel_hi:[1,0]
	v_pk_fma_f32 v[0:1], v[42:43], v[0:1], v[38:39]
	v_pk_fma_f32 v[4:5], v[40:41], v[2:3], v[36:37]
	v_pk_add_f32 v[2:3], v[14:15], v[0:1] op_sel_hi:[0,1]
	v_pk_add_f32 v[0:1], v[14:15], v[4:5] op_sel_hi:[0,1]
	global_store_dwordx4 v[22:23], v[0:3], off offset:1024
	s_nop 1
	v_pk_mul_f32 v[0:1], v[20:21], v[24:25] op_sel_hi:[1,0]
	v_pk_mul_f32 v[2:3], v[18:19], v[24:25] op_sel_hi:[1,0]
	v_pk_fma_f32 v[0:1], v[34:35], v[0:1], v[30:31]
	v_pk_fma_f32 v[4:5], v[32:33], v[2:3], v[28:29]
	v_pk_add_f32 v[2:3], v[14:15], v[0:1] op_sel_hi:[0,1]
	v_pk_add_f32 v[0:1], v[14:15], v[4:5] op_sel_hi:[0,1]
	global_store_dwordx4 v[22:23], v[0:3], off offset:1536
	s_branch .Lg2_next
